# scan phase: output-tile MFMA chain fed through a ring of operand register sets (reads up to four MFMAs ahead, counted waits) + filler amax via DPP, on top of the de-serialised chunk section
# speedup vs baseline: 1.0142x; 1.0024x over previous
; #define LAS __attribute__((address_space(3)))
; DI unsigned short f2bf1(float x) { return (unsigned short)(pk2(x, 0.f) & 0xffffu); }
; DI void phase_scan(int l, int wv, bool fill, bool last) {
;     ...
;             if (w >= 4 && outp) {
;                 const int tb = (w - 4) >> 1, vb = (w - 4) & 1;
;                 f32x16 acc;
; #pragma unroll
;                 for (int i = 0; i < 16; ++i) acc[i] = 0.f;
; #pragma unroll
;                 for (int ks = 0; ks < 4; ++ks) { const bf16x8v a = *(const LAS bf16x8v*)(L + O_PM + (tb * 32 + r32) * RS64 + (ks * 16 + 8 * hh) * 2), bv = tr_frag(L + O_V, RS64, ks * 16 + 8 * hh, vb * 32, lane);
;                     acc = __builtin_amdgcn_mfma_f32_32x32x16_bf16(a, bv, acc, 0, 0, 0); }
; #pragma unroll 4
;                 for (int ks = 0; ks < 8; ++ks) { const bf16x8v a = *(const LAS bf16x8v*)(L + O_QT + (tb * 32 + r32) * RS + (ks * 16 + 8 * hh) * 2), bs = *(const LAS bf16x8v*)(L + O_ST + (vb * 32 + r32) * RS + (ks * 16 + 8 * hh) * 2);
;                     acc = __builtin_amdgcn_mfma_f32_32x32x16_bf16(a, bs, acc, 0, 0, 0); }
;                 bf16* ob = (bf16*)F.OSC + ((size_t)dir * NTOK + row0) * DC + h * DK + vh * 64 + vb * 32 + r32;
; #pragma unroll
;                 for (int i = 0; i < 16; ++i) { const int t = tb * 32 + (i & 3) + 8 * (i >> 2) + 4 * hh; ob[(size_t)t * DC] = f2bf1(acc[i]); }
.LBB0_503:
	s_and_b64 s[60:61], s[58:59], s[60:61]
	s_andn2_b64 vcc, exec, s[60:61]
	s_cbranch_vccnz .LBB0_507
	v_add_u32_e32 v16, v191, v188
	ds_read_b128 v[16:19], v16 offset:61440
	ds_read_b64_tr_b16 v[20:21], v231 offset:52224
	ds_read_b64_tr_b16 v[22:23], v231 offset:52800
	ds_read_b128 v[208:211], v225 offset:61440
	ds_read_b64_tr_b16 v[232:233], v226 offset:52224
	ds_read_b64_tr_b16 v[234:235], v226 offset:52800
	ds_read_b128 v[32:35], v227 offset:61440
	ds_read_b64_tr_b16 v[36:37], v228 offset:52224
	ds_read_b64_tr_b16 v[38:39], v228 offset:52800
	ds_read_b128 v[40:43], v229 offset:61440
	ds_read_b64_tr_b16 v[44:45], v230 offset:52224
	ds_read_b64_tr_b16 v[46:47], v230 offset:52800
	ds_read_b128 v[48:51], v196
	ds_read_b128 v[52:55], v195
	s_waitcnt lgkmcnt(11)
	v_mfma_f32_32x32x16_bf16 v[16:31], v[16:19], v[20:23], 0
	ds_read_b128 v[56:59], v196 offset:32
	ds_read_b128 v[60:63], v195 offset:32
	s_waitcnt lgkmcnt(10)
	v_mfma_f32_32x32x16_bf16 v[16:31], v[208:211], v[232:235], v[16:31]
	ds_read_b128 v[208:211], v196 offset:64
	ds_read_b128 v[232:235], v195 offset:64
	s_waitcnt lgkmcnt(9)
	v_mfma_f32_32x32x16_bf16 v[16:31], v[32:35], v[36:39], v[16:31]
	ds_read_b128 v[32:35], v196 offset:96
	ds_read_b128 v[36:39], v195 offset:96
	s_waitcnt lgkmcnt(8)
	v_mfma_f32_32x32x16_bf16 v[16:31], v[40:43], v[44:47], v[16:31]
	ds_read_b128 v[40:43], v196 offset:128
	ds_read_b128 v[44:47], v195 offset:128
	s_waitcnt lgkmcnt(8)
	v_mfma_f32_32x32x16_bf16 v[16:31], v[48:51], v[52:55], v[16:31]
	ds_read_b128 v[48:51], v196 offset:160
	ds_read_b128 v[52:55], v195 offset:160
	s_waitcnt lgkmcnt(8)
	v_mfma_f32_32x32x16_bf16 v[16:31], v[56:59], v[60:63], v[16:31]
	ds_read_b128 v[56:59], v196 offset:192
	ds_read_b128 v[60:63], v195 offset:192
	s_waitcnt lgkmcnt(8)
	v_mfma_f32_32x32x16_bf16 v[16:31], v[208:211], v[232:235], v[16:31]
	ds_read_b128 v[208:211], v196 offset:224
	ds_read_b128 v[232:235], v195 offset:224
	s_waitcnt lgkmcnt(8)
	v_mfma_f32_32x32x16_bf16 v[16:31], v[32:35], v[36:39], v[16:31]
	s_waitcnt lgkmcnt(6)
	v_mfma_f32_32x32x16_bf16 v[16:31], v[40:43], v[44:47], v[16:31]
	s_waitcnt lgkmcnt(4)
	v_mfma_f32_32x32x16_bf16 v[16:31], v[48:51], v[52:55], v[16:31]
	s_waitcnt lgkmcnt(2)
	v_mfma_f32_32x32x16_bf16 v[16:31], v[56:59], v[60:63], v[16:31]
	s_waitcnt lgkmcnt(0)
	v_mfma_f32_32x32x16_bf16 v[16:31], v[208:211], v[232:235], v[16:31]
	s_nop 15
	s_ashr_i32 s61, s79, 31
	s_add_u32 s60, s79, s77
	s_addc_u32 s61, s61, 0
	s_lshl_b64 s[60:61], s[60:61], 11
	v_lshl_add_u64 v[208:209], v[166:167], 0, s[60:61]
	v_cvt_pk_bf16_f32 v16, v16, v129
	v_lshl_add_u64 v[210:211], v[208:209], 0, v[124:125]
	s_nop 4
	global_store_short v[210:211], v16, off
	v_cvt_pk_bf16_f32 v159, v17, v129
	v_lshl_add_u64 v[16:17], v[208:209], 0, v[126:127]
	global_store_short v[16:17], v159, off
	v_lshl_add_u64 v[16:17], v[208:209], 0, v[130:131]
	v_cvt_pk_bf16_f32 v18, v18, v129
	global_store_short v[16:17], v18, off
	v_lshl_add_u64 v[16:17], v[208:209], 0, v[132:133]
	v_cvt_pk_bf16_f32 v18, v19, v129
	global_store_short v[16:17], v18, off
	v_lshl_add_u64 v[16:17], v[208:209], 0, v[134:135]
	v_cvt_pk_bf16_f32 v18, v20, v129
	global_store_short v[16:17], v18, off
	v_lshl_add_u64 v[16:17], v[208:209], 0, v[136:137]
	v_cvt_pk_bf16_f32 v18, v21, v129
	global_store_short v[16:17], v18, off
	v_lshl_add_u64 v[16:17], v[208:209], 0, v[138:139]
	v_cvt_pk_bf16_f32 v18, v22, v129
	global_store_short v[16:17], v18, off
	v_lshl_add_u64 v[16:17], v[208:209], 0, v[140:141]
	v_cvt_pk_bf16_f32 v18, v23, v129
	global_store_short v[16:17], v18, off
	v_lshl_add_u64 v[16:17], v[208:209], 0, v[142:143]
	v_cvt_pk_bf16_f32 v18, v24, v129
	global_store_short v[16:17], v18, off
	v_lshl_add_u64 v[16:17], v[208:209], 0, v[144:145]
	v_cvt_pk_bf16_f32 v18, v25, v129
	global_store_short v[16:17], v18, off
	v_lshl_add_u64 v[16:17], v[208:209], 0, v[146:147]
	v_cvt_pk_bf16_f32 v18, v26, v129
	global_store_short v[16:17], v18, off
	v_lshl_add_u64 v[16:17], v[208:209], 0, v[148:149]
	v_cvt_pk_bf16_f32 v18, v27, v129
	global_store_short v[16:17], v18, off
	v_lshl_add_u64 v[16:17], v[208:209], 0, v[150:151]
	v_cvt_pk_bf16_f32 v18, v28, v129
	global_store_short v[16:17], v18, off
	v_lshl_add_u64 v[16:17], v[208:209], 0, v[152:153]
	v_cvt_pk_bf16_f32 v18, v29, v129
	global_store_short v[16:17], v18, off
	v_lshl_add_u64 v[16:17], v[208:209], 0, v[154:155]
	v_cvt_pk_bf16_f32 v18, v30, v129
	global_store_short v[16:17], v18, off
	v_lshl_add_u64 v[16:17], v[208:209], 0, v[156:157]
	v_cvt_pk_bf16_f32 v18, v31, v129
	global_store_short v[16:17], v18, off
